# convert loop: both tile loads in flight (global_load); F1L GEMM unit-to-workgroup bit permutation so row-sharing units run on one XCD (L2 write merging)
# speedup vs baseline: 1.0436x; 1.0252x over previous
.LBB0_43:
	s_lshl_b32 s18, s36, 6
	v_lshlrev_b32_e32 v3, 4, v2
	s_and_b32 s36, s18, 0x3c0
	s_lshl_b64 s[18:19], s[26:27], 2
	v_and_b32_e32 v14, 0xf0, v3
	v_ashrrev_i32_e32 v3, 4, v2
	s_waitcnt lgkmcnt(0)
	s_add_u32 s14, s14, s18
	v_add_u32_e32 v18, s36, v3
	s_addc_u32 s15, s15, s19
	v_ashrrev_i32_e32 v19, 31, v18
	v_lshl_add_u64 v[4:5], s[14:15], 0, v[14:15]
	v_mul_lo_u32 v23, s16, v19
	v_mul_lo_u32 v24, s17, v18
	v_mad_u64_u32 v[18:19], s[14:15], s16, v18, 0
	v_add3_u32 v19, v19, v23, v24
	v_lshl_add_u64 v[18:19], v[18:19], 2, v[4:5]
	global_load_dwordx4 v[24:27], v[18:19], off
	v_add_u32_e32 v18, 0x200, v2
	v_ashrrev_i32_e32 v23, 4, v18
	v_add_u32_e32 v14, s59, v14
	v_add_u32_e32 v28, s36, v23
	v_mad_u64_u32 v[18:19], s[14:15], v3, s60, v[14:15]
	v_ashrrev_i32_e32 v3, 31, v28
	v_mul_lo_u32 v19, s17, v28
	v_mad_u64_u32 v[28:29], s[14:15], s16, v28, 0
	v_mul_lo_u32 v3, s16, v3
	v_add3_u32 v29, v29, v3, v19
	v_lshl_add_u64 v[4:5], v[28:29], 2, v[4:5]
	global_load_dwordx4 v[200:203], v[4:5], off
	s_lshl_b32 s26, s36, 1
	s_mov_b64 s[36:37], -1
	s_waitcnt vmcnt(1) lgkmcnt(0)
	ds_write2_b32 v18, v24, v25 offset1:1
	ds_write2_b32 v18, v26, v27 offset0:2 offset1:3
	v_ashrrev_i32_e32 v4, 3, v2
	v_lshlrev_b32_e32 v2, 3, v2
	v_and_b32_e32 v18, 56, v2
	v_lshlrev_b32_e32 v19, 2, v4
	v_ashrrev_i32_e32 v5, 31, v4
	v_mul_u32_u24_e32 v28, 0x104, v18
	v_lshlrev_b64 v[2:3], 11, v[4:5]
	v_mad_u64_u32 v[4:5], s[16:17], v23, s60, v[14:15]
	v_add3_u32 v19, s59, v28, v19
	v_add_u32_e32 v23, 0x400, v19
	v_lshlrev_b32_e32 v14, 1, v18
	v_lshl_add_u64 v[2:3], s[12:13], 0, v[2:3]
	v_lshl_add_u64 v[2:3], v[2:3], 0, s[26:27]
	v_lshl_add_u64 v[28:29], v[2:3], 0, v[14:15]
	s_waitcnt vmcnt(0) lgkmcnt(0)
	ds_write2_b32 v4, v200, v201 offset1:1
	ds_write2_b32 v4, v202, v203 offset0:2 offset1:3
	s_waitcnt lgkmcnt(0)
	s_barrier
	ds_read2_b32 v[4:5], v19 offset1:65
	ds_read2_b32 v[18:19], v19 offset0:130 offset1:195
	ds_read2_b32 v[24:25], v23 offset0:4 offset1:69
	ds_read2_b32 v[26:27], v23 offset0:134 offset1:199
	s_waitcnt lgkmcnt(3)
	s_nop 1
	v_cvt_pk_bf16_f32 v2, v4, v5
	s_waitcnt lgkmcnt(2)
	s_nop 1
	v_cvt_pk_bf16_f32 v3, v18, v19
	s_waitcnt lgkmcnt(1)
	s_nop 1
	v_cvt_pk_bf16_f32 v4, v24, v25
	s_waitcnt lgkmcnt(0)
	s_nop 1
	v_cvt_pk_bf16_f32 v5, v26, v27
	global_store_dwordx4 v[28:29], v[2:5], off
	s_barrier
	s_branch .LBB0_57

.LBB0_160:
	s_or_b64 exec, exec, s[6:7]
	s_lshl_b32 s7, s2, 3
	s_lshl_b32 s18, s20, 3
	s_cmpk_gt_i32 s2, 0x10ff
	v_writelane_b32 v253, s7, 0
	s_cselect_b64 s[8:9], -1, 0
	v_writelane_b32 v253, s8, 1
	s_mul_i32 s6, s21, s20
	s_mov_b32 s31, 0
	v_writelane_b32 v253, s9, 2
	s_add_u32 s8, s22, 0x200
	s_addc_u32 s9, s23, 0
	v_writelane_b32 v253, s8, 3
	v_mov_b32_e32 v234, 0x358637bd
	v_mov_b32_e32 v233, 1
	v_writelane_b32 v253, s9, 4
	s_add_u32 s8, s22, 0x1000
	s_addc_u32 s9, s23, 0
	v_writelane_b32 v253, s8, 5
	v_mov_b32_e32 v220, 0x7f800000
	v_not_b32_e32 v252, 31
	v_writelane_b32 v253, s9, 6
	s_add_u32 s8, s22, 0x1100
	s_addc_u32 s9, s23, 0
	v_writelane_b32 v253, s8, 7
	v_mov_b32_e32 v228, 0x7fc00000
	v_mov_b64_e32 v[244:245], 0x400
	v_writelane_b32 v253, s9, 8
	s_add_u32 s8, s22, 0x1200
	s_addc_u32 s9, s23, 0
	v_writelane_b32 v253, s8, 9
	v_mov_b32_e32 v235, 0x80
	v_mov_b64_e32 v[248:249], 0x100
	v_writelane_b32 v253, s9, 10
	s_add_u32 s8, s22, 0x1300
	s_addc_u32 s9, s23, 0
	v_writelane_b32 v253, s8, 11
	s_cmp_eq_u32 s3, 15
	v_mov_b64_e32 v[250:251], 0xff
	v_writelane_b32 v253, s9, 12
	s_cselect_b64 s[8:9], -1, 0
	v_writelane_b32 v253, s8, 13
	s_cmp_eq_u32 s3, 14
	s_mov_b32 s90, 0x800000
	v_writelane_b32 v253, s9, 14
	s_cselect_b64 s[8:9], -1, 0
	v_writelane_b32 v253, s8, 15
	s_cmp_eq_u32 s3, 13
	s_mov_b32 s91, 0xe010000
	v_writelane_b32 v253, s9, 16
	s_cselect_b64 s[8:9], -1, 0
	v_writelane_b32 v253, s8, 17
	s_cmp_eq_u32 s3, 12
	s_mov_b32 s92, 0xeac00000
	v_writelane_b32 v253, s9, 18
	s_cselect_b64 s[8:9], -1, 0
	v_writelane_b32 v253, s8, 19
	s_cmp_eq_u32 s3, 11
	s_mov_b32 s93, 0xece00000
	v_writelane_b32 v253, s9, 20
	s_cselect_b64 s[8:9], -1, 0
	v_writelane_b32 v253, s8, 21
	s_cmp_eq_u32 s3, 10
	s_mov_b32 s94, 0xeac01000
	v_writelane_b32 v253, s9, 22
	s_cselect_b64 s[8:9], -1, 0
	v_writelane_b32 v253, s8, 23
	s_cmp_eq_u32 s3, 9
	s_mov_b32 s95, 0xece01000
	v_writelane_b32 v253, s9, 24
	s_cselect_b64 s[8:9], -1, 0
	v_writelane_b32 v253, s8, 25
	s_cmp_eq_u32 s3, 8
	s_mov_b32 s96, 0x16850000
	v_writelane_b32 v253, s9, 26
	s_cselect_b64 s[8:9], -1, 0
	v_writelane_b32 v253, s8, 27
	s_cmp_eq_u32 s3, 7
	s_mov_b32 s97, 0x16860000
	v_writelane_b32 v253, s9, 28
	s_cselect_b64 s[8:9], -1, 0
	v_writelane_b32 v253, s8, 29
	s_cmp_eq_u32 s3, 6
	s_mov_b64 s[38:39], 0x100
	v_writelane_b32 v253, s9, 30
	s_cselect_b64 s[8:9], -1, 0
	v_writelane_b32 v253, s8, 31
	s_cmp_eq_u32 s3, 5
	s_mov_b32 s28, 0x3b800000
	v_writelane_b32 v253, s9, 32
	s_cselect_b64 s[8:9], -1, 0
	v_writelane_b32 v253, s8, 33
	s_cmp_eq_u32 s3, 4
	s_mov_b32 s30, s31
	v_writelane_b32 v253, s9, 34
	s_cselect_b64 s[8:9], -1, 0
	v_writelane_b32 v253, s8, 35
	s_cmp_eq_u32 s3, 3
	s_nop 0
	v_writelane_b32 v253, s9, 36
	s_cselect_b64 s[8:9], -1, 0
	v_writelane_b32 v253, s8, 37
	s_cmp_eq_u32 s3, 2
	s_nop 0
	v_writelane_b32 v253, s9, 38
	s_cselect_b64 s[8:9], -1, 0
	v_writelane_b32 v253, s8, 39
	s_cmp_eq_u32 s3, 1
	s_nop 0
	v_writelane_b32 v253, s9, 40
	s_cselect_b64 s[8:9], -1, 0
	v_writelane_b32 v253, s8, 41
	s_cmp_eq_u32 s3, 0
	s_nop 0
	v_writelane_b32 v253, s9, 42
	s_cselect_b64 s[8:9], -1, 0
	s_lshl_b32 s3, s3, 8
	s_add_u32 s3, s22, s3
	v_writelane_b32 v253, s8, 43
	s_addc_u32 s7, s23, 0
	s_nop 0
	v_writelane_b32 v253, s9, 44
	s_add_u32 s8, s3, 0x1400
	s_addc_u32 s9, s7, 0
	v_writelane_b32 v253, s8, 45
	s_nop 1
	v_writelane_b32 v253, s9, 46
	s_add_u32 s8, s3, 0x2400
	s_addc_u32 s9, s7, 0
	v_writelane_b32 v253, s8, 47
	s_nop 1
	v_writelane_b32 v253, s9, 48
	s_add_u32 s8, s22, 0x3400
	s_addc_u32 s9, s23, 0
	v_writelane_b32 v253, s8, 49
	s_nop 1
	v_writelane_b32 v253, s9, 50
	s_add_u32 s8, s22, 0x3500
	s_addc_u32 s9, s23, 0
	v_writelane_b32 v253, s8, 51
	s_cmpk_gt_i32 s2, 0xbaf
	s_nop 0
	v_writelane_b32 v253, s9, 52
	s_cselect_b64 s[8:9], -1, 0
	s_add_i32 s3, s2, 0xfffff450
	v_writelane_b32 v253, s8, 53
	s_cmpk_lt_u32 s3, 0x220
	s_nop 0
	v_writelane_b32 v253, s9, 54
	s_cselect_b64 s[8:9], -1, 0
	s_and_b32 s7, s2, 7
	s_lshr_b32 s3, s3, 3
	s_mulk_i32 s7, 0x44
	v_writelane_b32 v253, s8, 55
	s_add_i32 s7, s7, s3
	s_and_b32 s3, s7, 7
	v_writelane_b32 v253, s9, 56
	v_writelane_b32 v253, s3, 57
	s_lshl_b32 s3, s3, 19
	s_lshr_b32 s7, s7, 3
	v_writelane_b32 v253, s3, 58
	v_writelane_b32 v253, s7, 59
	s_lshl_b32 s3, s7, 19
	v_writelane_b32 v253, s3, 60
	s_ashr_i32 s3, s2, 31
	s_lshr_b32 s7, s3, 29
	s_add_i32 s7, s2, s7
	s_ashr_i32 s8, s7, 3
	s_and_b32 s7, s7, -8
	s_sub_i32 s7, s2, s7
	s_cmp_lt_i32 s7, 0
	s_movk_i32 s9, 0x177
	s_cselect_b32 s9, s9, 0x176
	s_mul_i32 s9, s9, s7
	s_add_i32 s9, s9, s8
	s_mul_hi_i32 s10, s9, 0x2e8ba2e9
	s_lshr_b32 s11, s10, 31
	s_ashr_i32 s10, s10, 6
	s_add_i32 s10, s10, s11
	s_lshl_b32 s11, s10, 3
	s_sub_i32 s12, 0x44, s11
	s_mulk_i32 s10, 0x160
	s_min_u32 s12, s12, 8
	s_sub_i32 s10, s9, s10
	s_ashr_i32 s21, s20, 31
	s_andn2_b32 s100, s2, 0x3e
	s_bfe_u32 s101, s2, 0x30003
	s_lshl_b32 s101, s101, 1
	s_or_b32 s100, s100, s101
	s_bfe_u32 s101, s2, 0x20001
	s_lshl_b32 s101, s101, 4
	s_or_b32 s100, s100, s101
	s_cmpk_lt_i32 s2, 0x200
	s_cselect_b64 s[14:15], -1, 0
	v_writelane_b32 v253, s14, 61
	s_ashr_i32 s9, s2, 7
	s_bfe_u32 s13, s2, 0x10006
	v_writelane_b32 v253, s15, 62
	v_writelane_b32 v253, s9, 63
	s_and_b32 s9, s100, 63
	v_writelane_b32 v254, s9, 0
	v_writelane_b32 v254, s13, 1
	s_lshl_b32 s13, s13, 17
	s_bfe_u32 s9, s100, 0x20004
	v_writelane_b32 v254, s13, 2
	s_lshl_b32 s13, s2, 8
	s_mulk_i32 s9, 0x1100
	v_writelane_b32 v254, s13, 3
	s_lshl_b32 s13, s100, 8
	s_and_b32 s13, s13, 0xe00
	s_add_i32 s9, s9, s13
	s_lshl_b32 s13, s100, 5
	s_and_b32 s13, s13, 32
	s_or_b32 s9, s9, s13
	s_lshl_b32 s9, s9, 11
	s_add_i32 s9, s9, 0x80000
	s_lshl_b64 s[14:15], s[2:3], 2
	v_writelane_b32 v254, s9, 4
	s_and_b32 s14, s14, 0xfffffe00
	v_writelane_b32 v254, s14, 5
	s_not_b32 s13, s2
	v_cvt_f32_ubyte0_e32 v1, s12
	v_writelane_b32 v254, s15, 6
	s_add_i32 s14, s20, s13
	s_cmp_lt_i32 s14, 32
	s_cselect_b64 s[16:17], -1, 0
	v_writelane_b32 v254, s16, 7
	s_ashr_i32 s15, s14, 31
	s_ashr_i32 s9, s14, 3
	v_writelane_b32 v254, s17, 8
	s_lshl_b64 s[16:17], s[14:15], 6
	s_and_b32 s16, s16, 0xfffffe00
	v_writelane_b32 v254, s16, 9
	v_cvt_f32_i32_e32 v0, s10
	v_rcp_iflag_f32_e32 v2, v1
	v_writelane_b32 v254, s17, 10
	v_writelane_b32 v254, s9, 11
	s_bfe_u32 s9, s14, 0x10002
	v_writelane_b32 v254, s14, 12
	v_mul_f32_e32 v2, v0, v2
	v_trunc_f32_e32 v2, v2
	v_writelane_b32 v254, s15, 13
	s_and_b32 s14, s14, 3
	v_writelane_b32 v254, s14, 14
	v_writelane_b32 v254, s9, 15
	s_lshl_b32 s9, s9, 17
	s_cmpk_lt_i32 s2, 0x400
	v_writelane_b32 v254, s9, 16
	s_cselect_b64 s[14:15], -1, 0
	v_writelane_b32 v254, s14, 17
	s_lshl_b64 s[24:25], s[2:3], 16
	s_add_u32 s9, s22, 0xc000
	v_writelane_b32 v254, s15, 18
	v_writelane_b32 v254, s9, 19
	s_addc_u32 s9, s23, 0
	v_writelane_b32 v254, s9, 20
	s_add_u32 s9, s22, 0x4000
	v_writelane_b32 v254, s9, 21
	s_addc_u32 s9, s23, 0
	s_cmpk_lt_i32 s2, 0x100
	v_writelane_b32 v254, s9, 22
	s_cselect_b64 s[14:15], -1, 0
	s_lshr_b32 s9, s7, 31
	s_or_b32 s9, s9, 32
	s_mul_i32 s7, s9, s7
	s_add_i32 s7, s7, s8
	s_ashr_i32 s8, s7, 31
	s_lshr_b32 s8, s8, 27
	s_add_i32 s8, s7, s8
	v_writelane_b32 v254, s14, 23
	s_and_b32 s9, s8, 0xffffffe0
	s_ashr_i32 s8, s8, 5
	v_writelane_b32 v254, s15, 24
	s_lshl_b32 s14, s8, 3
	s_sub_i32 s8, 64, s14
	s_min_u32 s15, s8, 8
	s_ashr_i32 s8, s10, 30
	v_fma_f32 v0, -v2, v1, v0
	s_sub_i32 s7, s7, s9
	s_or_b32 s16, s8, 1
	v_cmp_ge_f32_e64 s[8:9], |v0|, v1
	v_cvt_i32_f32_e32 v0, v2
	s_and_b64 s[8:9], s[8:9], exec
	s_cselect_b32 s8, s16, 0
	v_cvt_f32_ubyte0_e32 v1, s15
	v_readfirstlane_b32 s9, v0
	s_add_i32 s8, s9, s8
	s_mul_i32 s9, s8, s12
	s_sub_i32 s9, s10, s9
	s_sext_i32_i16 s9, s9
	s_add_i32 s16, s11, s9
	v_cvt_f32_i32_e32 v0, s7
	v_rcp_iflag_f32_e32 v2, v1
	s_bfe_i64 s[10:11], s[8:9], 0x100000
	s_lshl_b64 s[10:11], s[10:11], 19
	v_writelane_b32 v254, s10, 25
	s_ashr_i32 s17, s16, 31
	v_mul_f32_e32 v2, v0, v2
	v_writelane_b32 v254, s11, 26
	s_mov_b32 s10, s16
	v_writelane_b32 v254, s10, 27
	v_trunc_f32_e32 v2, v2
	s_ashr_i32 s9, s7, 30
	v_writelane_b32 v254, s11, 28
	s_lshl_b64 s[10:11], s[16:17], 19
	v_fma_f32 v0, -v2, v1, v0
	v_writelane_b32 v254, s10, 29
	s_or_b32 s9, s9, 1
	s_movk_i32 s17, 0x1800
	v_writelane_b32 v254, s11, 30
	v_cmp_ge_f32_e64 s[10:11], |v0|, v1
	s_and_b64 s[10:11], s[10:11], exec
	s_load_dword s10, s[0:1], 0xc0
	v_cvt_i32_f32_e32 v0, v2
	s_barrier
	v_mbcnt_lo_u32_b32 v1, -1, 0
	v_mbcnt_hi_u32_b32 v223, -1, v1
	s_waitcnt lgkmcnt(0)
	s_mul_i32 s6, s6, s10
	v_writelane_b32 v254, s6, 31
	s_sext_i32_i16 s6, s8
	v_writelane_b32 v254, s6, 32
	s_cselect_b32 s6, s9, 0
	v_readfirstlane_b32 s8, v0
	s_add_i32 s6, s8, s6
	s_mul_i32 s8, s6, s15
	s_sub_i32 s7, s7, s8
	s_sext_i32_i8 s7, s7
	s_add_i32 s14, s14, s7
	s_ashr_i32 s7, s14, 4
	s_mul_i32 s7, s7, 17
	s_and_b32 s8, s14, 15
	s_add_i32 s7, s8, s7
	s_add_i32 s8, s7, 1
	s_sext_i32_i8 s7, s6
	v_writelane_b32 v254, s7, 33
	s_bfe_i64 s[6:7], s[6:7], 0x80000
	s_lshl_b64 s[6:7], s[6:7], 19
	v_writelane_b32 v254, s6, 34
	s_ashr_i32 s9, s8, 31
	s_ashr_i32 s19, s18, 31
	v_writelane_b32 v254, s7, 35
	s_lshl_b32 s6, s2, 6
	v_writelane_b32 v254, s6, 36
	s_lshl_b32 s6, s20, 6
	v_writelane_b32 v254, s6, 37
	s_add_i32 s6, s20, s100
	v_writelane_b32 v254, s6, 38
	s_lshl_b32 s6, s6, 8
	v_writelane_b32 v254, s6, 39
	s_lshl_b32 s6, s20, 8
	v_writelane_b32 v254, s6, 40
	s_mov_b32 s6, s8
	v_writelane_b32 v254, s6, 41
	v_and_b32_e32 v224, 64, v223
	v_mov_b32_e32 v0, 0
	v_writelane_b32 v254, s7, 42
	s_lshl_b64 s[6:7], s[8:9], 19
	v_writelane_b32 v254, s6, 43
	v_add_u32_e32 v225, 64, v224
	v_xor_b32_e32 v243, 16, v223
	v_writelane_b32 v254, s7, 44
	s_lshl_b64 s[6:7], s[18:19], 6
	v_writelane_b32 v254, s6, 45
	v_xor_b32_e32 v222, 8, v223
	v_xor_b32_e32 v229, 4, v223
	v_writelane_b32 v254, s7, 46
	s_mov_b32 s6, s18
	v_writelane_b32 v254, s6, 47
	v_xor_b32_e32 v230, 2, v223
	v_xor_b32_e32 v231, 1, v223
	v_writelane_b32 v254, s7, 48
	s_lshl_b64 s[6:7], s[18:19], 11
	v_writelane_b32 v254, s6, 49
	s_add_u32 s8, s20, s2
	s_addc_u32 s9, s21, s3
	v_writelane_b32 v254, s7, 50
	s_lshl_b32 s6, s20, 1
	s_add_i32 s6, s13, s6
	v_writelane_b32 v254, s6, 51
	s_lshl_b64 s[6:7], s[8:9], 5
	v_writelane_b32 v254, s6, 52
	s_movk_i32 s18, 0x1ff
	s_nop 0
	v_writelane_b32 v254, s7, 53
	s_lshl_b64 s[6:7], s[20:21], 5
	v_writelane_b32 v254, s6, 54
	s_nop 1
	v_writelane_b32 v254, s7, 55
	s_add_u32 s6, s24, 0x29a18080
	v_writelane_b32 v254, s24, 56
	s_addc_u32 s7, s25, 0
	s_nop 0
	v_writelane_b32 v254, s25, 57
	v_writelane_b32 v254, s6, 58
	s_mov_b64 s[24:25], 0x80
	s_nop 0
	v_writelane_b32 v254, s7, 59
	s_lshl_b64 s[6:7], s[20:21], 16
	v_writelane_b32 v254, s6, 60
	s_nop 1
	v_writelane_b32 v254, s7, 61
	v_writelane_b32 v254, s8, 62
	s_lshl_b64 s[6:7], s[8:9], 16
	s_add_u32 s6, s6, 0x29a10000
	v_writelane_b32 v255, s6, 0
	s_addc_u32 s6, s7, 0
	v_writelane_b32 v255, s6, 1
	s_add_i32 s6, 0, 0x23ff0
	v_writelane_b32 v255, s6, 2
	s_add_i32 s6, 0, 0x23ff4
	v_writelane_b32 v255, s6, 3
	s_add_i32 s6, 0, 0x13c00
	v_writelane_b32 v255, s6, 4
	s_add_i32 s6, 0, 0x11800
	v_writelane_b32 v255, s6, 5
	s_add_i32 s6, 0, 0x1c400
	v_writelane_b32 v255, s6, 6
	s_add_i32 s6, 0, 0x1c500
	v_writelane_b32 v255, s6, 7
	s_add_i32 s6, 0, 0x1c800
	v_writelane_b32 v255, s6, 8
	s_add_i32 s6, 0, 0x1c700
	v_writelane_b32 v254, s9, 63
	v_writelane_b32 v255, s6, 9
	s_mov_b64 s[8:9], 0x2000
	v_writelane_b32 v255, s8, 10
	s_add_i32 s33, 0, 0x10000
	s_add_i32 s16, 0, 0x23ff8
	s_add_i32 s19, 0, 0x1c600
	s_add_i32 s7, 0, 0x1c900
	s_add_i32 s29, 0, 0x1ce00
	v_writelane_b32 v255, s9, 11
	s_mov_b64 s[8:9], 0x180
	s_branch .LBB0_164

.LBB0_180:
	s_ashr_i32 s37, s36, 31
	s_and_b32 s30, s6, 0x3c0
	s_lshl_b64 s[34:35], s[36:37], 2
	s_add_u32 s34, s40, s34
	v_lshlrev_b32_e32 v2, 4, v1
	s_addc_u32 s35, s41, s35
	v_and_b32_e32 v6, 0xf0, v2
	v_mov_b32_e32 v7, v0
	v_lshl_add_u64 v[8:9], s[34:35], 0, v[6:7]
	v_ashrrev_i32_e32 v7, 4, v1
	v_add_u32_e32 v2, s30, v7
	v_ashrrev_i32_e32 v3, 31, v2
	v_mul_lo_u32 v4, s42, v3
	v_mul_lo_u32 v5, s43, v2
	v_mad_u64_u32 v[2:3], s[34:35], s42, v2, 0
	v_add3_u32 v3, v3, v4, v5
	v_lshl_add_u64 v[2:3], v[2:3], 2, v[8:9]
	global_load_dwordx4 v[2:5], v[2:3], off
	v_add_u32_e32 v10, 0x200, v1
	v_ashrrev_i32_e32 v14, 4, v10
	v_add_u32_e32 v6, s33, v6
	v_add_u32_e32 v12, s30, v14
	s_movk_i32 s36, 0x104
	v_mad_u64_u32 v[10:11], s[34:35], v7, s36, v[6:7]
	v_ashrrev_i32_e32 v7, 31, v12
	v_mul_lo_u32 v11, s43, v12
	v_mad_u64_u32 v[12:13], s[34:35], s42, v12, 0
	v_mul_lo_u32 v7, s42, v7
	v_add3_u32 v13, v13, v7, v11
	v_lshl_add_u64 v[8:9], v[12:13], 2, v[8:9]
	global_load_dwordx4 v[200:203], v[8:9], off
	v_mad_u64_u32 v[6:7], s[34:35], v14, s36, v[6:7]
	s_lshl_b32 s30, s30, 1
	v_mov_b32_e32 v11, v0
	s_add_i32 s18, s18, s20
	s_waitcnt vmcnt(1) lgkmcnt(0)
	ds_write2_b32 v10, v2, v3 offset1:1
	ds_write2_b32 v10, v4, v5 offset0:2 offset1:3
	v_ashrrev_i32_e32 v8, 3, v1
	v_lshlrev_b32_e32 v1, 3, v1
	v_and_b32_e32 v1, 56, v1
	v_lshlrev_b32_e32 v12, 2, v8
	v_mul_u32_u24_e32 v13, 0x104, v1
	v_lshlrev_b32_e32 v10, 1, v1
	v_add3_u32 v1, s33, v13, v12
	v_add_u32_e32 v12, 0x400, v1
	v_ashrrev_i32_e32 v9, 31, v8
	v_lshlrev_b64 v[8:9], 11, v[8:9]
	v_lshl_add_u64 v[8:9], s[26:27], 0, v[8:9]
	v_readlane_b32 s26, v254, 37
	s_add_i32 s6, s6, s26
	v_lshl_add_u64 v[8:9], v[8:9], 0, s[30:31]
	s_cmpk_lt_i32 s18, 0x1100
	v_lshl_add_u64 v[8:9], v[8:9], 0, v[10:11]
	s_waitcnt vmcnt(0) lgkmcnt(0)
	ds_write2_b32 v6, v200, v201 offset1:1
	ds_write2_b32 v6, v202, v203 offset0:2 offset1:3
	s_waitcnt lgkmcnt(0)
	s_barrier
	ds_read2_b32 v[2:3], v1 offset1:65
	ds_read2_b32 v[4:5], v1 offset0:130 offset1:195
	ds_read2_b32 v[6:7], v12 offset0:4 offset1:69
	ds_read2_b32 v[12:13], v12 offset0:134 offset1:199
	s_waitcnt lgkmcnt(3)
	s_nop 1
	v_cvt_pk_bf16_f32 v2, v2, v3
	s_waitcnt lgkmcnt(2)
	s_nop 1
	v_cvt_pk_bf16_f32 v3, v4, v5
	s_waitcnt lgkmcnt(1)
	s_nop 1
	v_cvt_pk_bf16_f32 v4, v6, v7
	s_waitcnt lgkmcnt(0)
	s_nop 1
	v_cvt_pk_bf16_f32 v5, v12, v13
	global_store_dwordx4 v[8:9], v[2:5], off
	s_barrier
	s_cbranch_scc0 .LBB0_189

	.amdhsa_kernel _Z8mega_fwd6Params
		.amdhsa_group_segment_fixed_size 0
		.amdhsa_private_segment_fixed_size 0
		.amdhsa_kernarg_size 440
		.amdhsa_user_sgpr_count 2
		.amdhsa_user_sgpr_dispatch_ptr 0
		.amdhsa_user_sgpr_queue_ptr 0
		.amdhsa_user_sgpr_kernarg_segment_ptr 1
		.amdhsa_user_sgpr_dispatch_id 0
		.amdhsa_user_sgpr_kernarg_preload_length 0
		.amdhsa_user_sgpr_kernarg_preload_offset 0
		.amdhsa_user_sgpr_private_segment_size 0
		.amdhsa_uses_dynamic_stack 0
		.amdhsa_enable_private_segment 0
		.amdhsa_system_sgpr_workgroup_id_x 1
		.amdhsa_system_sgpr_workgroup_id_y 0
		.amdhsa_system_sgpr_workgroup_id_z 0
		.amdhsa_system_sgpr_workgroup_info 0
		.amdhsa_system_vgpr_workitem_id 2
		.amdhsa_next_free_vgpr 256
		.amdhsa_next_free_sgpr 102
		.amdhsa_accum_offset 256
		.amdhsa_reserve_vcc 1
		.amdhsa_float_round_mode_32 0
		.amdhsa_float_round_mode_16_64 0
		.amdhsa_float_denorm_mode_32 3
		.amdhsa_float_denorm_mode_16_64 3
		.amdhsa_dx10_clamp 1
		.amdhsa_ieee_mode 1
		.amdhsa_fp16_overflow 0
		.amdhsa_tg_split 0
		.amdhsa_exception_fp_ieee_invalid_op 0
		.amdhsa_exception_fp_denorm_src 0
		.amdhsa_exception_fp_ieee_div_zero 0
		.amdhsa_exception_fp_ieee_overflow 0
		.amdhsa_exception_fp_ieee_underflow 0
		.amdhsa_exception_fp_ieee_inexact 0
		.amdhsa_exception_int_div_zero 0
	.end_amdhsa_kernel

amdhsa.kernels:
  - .agpr_count:     0
    .args:
      - .offset:         0
        .size:           184
        .value_kind:     by_value
      - .offset:         184
        .size:           4
        .value_kind:     hidden_block_count_x
      - .offset:         188
        .size:           4
        .value_kind:     hidden_block_count_y
      - .offset:         192
        .size:           4
        .value_kind:     hidden_block_count_z
      - .offset:         196
        .size:           2
        .value_kind:     hidden_group_size_x
      - .offset:         198
        .size:           2
        .value_kind:     hidden_group_size_y
      - .offset:         200
        .size:           2
        .value_kind:     hidden_group_size_z
      - .offset:         202
        .size:           2
        .value_kind:     hidden_remainder_x
      - .offset:         204
        .size:           2
        .value_kind:     hidden_remainder_y
      - .offset:         206
        .size:           2
        .value_kind:     hidden_remainder_z
      - .offset:         224
        .size:           8
        .value_kind:     hidden_global_offset_x
      - .offset:         232
        .size:           8
        .value_kind:     hidden_global_offset_y
      - .offset:         240
        .size:           8
        .value_kind:     hidden_global_offset_z
      - .offset:         248
        .size:           2
        .value_kind:     hidden_grid_dims
      - .offset:         272
        .size:           8
        .value_kind:     hidden_multigrid_sync_arg
      - .offset:         304
        .size:           4
        .value_kind:     hidden_dynamic_lds_size
    .group_segment_fixed_size: 0
    .kernarg_segment_align: 8
    .kernarg_segment_size: 440
    .language:       OpenCL C
    .language_version:
      - 2
      - 0
    .max_flat_workgroup_size: 512
    .name:           _Z8mega_fwd6Params
    .private_segment_fixed_size: 0
    .sgpr_count:     108
    .sgpr_spill_count: 169
    .symbol:         _Z8mega_fwd6Params.kd
    .uniform_work_group_size: 1
    .uses_dynamic_stack: false
    .vgpr_count:     256
    .vgpr_spill_count: 0
    .wavefront_size: 64
